# phase-5 item starts: full vmcnt drain before the thread-id asm replaced by s_nop (only the previous item's output stores were outstanding)
# baseline (speedup 1.0000x reference)
.LBB0_181:
	s_cmpk_gt_i32 s18, 0x5ff
	s_mov_b64 s[6:7], -1
	s_cbranch_scc0 .LBB0_187
	s_add_i32 s6, s18, 0xfffffa00
	s_mul_i32 s7, s6, 0xcccd
	s_lshr_b32 s6, s6, 6
	s_lshr_b32 s40, s7, 25
	s_mul_i32 s7, s6, 0xcd
	s_bfe_u32 s7, s7, 0x5000b
	s_mul_i32 s7, s7, 10
	s_sub_i32 s6, s6, s7
	s_nop 0
	v_mov_b32_e32 v53, v154
	s_and_b32 s37, s6, 0xff
	s_and_b32 s41, s18, 63
	s_lshl_b32 s34, s40, 12
	v_readfirstlane_b32 s6, v53
	s_lshl_b32 s35, s41, 6
	s_ashr_i32 s36, s6, 2
	s_or_b32 s34, s34, s35
	s_and_b32 s35, s36, -16
	s_ashr_i32 s6, s35, 31
	s_add_u32 s72, s35, s34
	v_and_b32_e32 v60, 63, v53
	s_addc_u32 s6, s6, 0
	s_lshl_b32 s34, s37, 6
	v_or_b32_e32 v0, s34, v60
	s_mul_hi_i32 s38, s72, 0x280
	s_mul_i32 s39, s72, 0x280
	v_or_b32_e32 v2, s39, v0
	v_mov_b32_e32 v3, s38
	v_lshlrev_b64 v[2:3], 1, v[2:3]
	v_lshl_add_u64 v[4:5], s[50:51], 0, v[2:3]
	v_add_co_u32_e32 v6, vcc, s88, v4
	v_lshl_add_u64 v[2:3], s[52:53], 0, v[2:3]
	s_nop 0
	v_addc_co_u32_e32 v7, vcc, 0, v5, vcc
	v_add_co_u32_e32 v8, vcc, s88, v2
	s_movk_i32 s42, 0x2000
	s_nop 0
	v_addc_co_u32_e32 v9, vcc, 0, v3, vcc
	s_add_u32 s39, s39, 0x1400
	s_barrier
	global_load_ushort v93, v[4:5], off
	global_load_ushort v91, v[4:5], off offset:1280
	global_load_ushort v89, v[4:5], off offset:2560
	global_load_ushort v87, v[4:5], off offset:3840
	global_load_ushort v94, v[2:3], off
	global_load_ushort v92, v[2:3], off offset:1280
	global_load_ushort v90, v[2:3], off offset:2560
	global_load_ushort v88, v[2:3], off offset:3840
	global_load_ushort v85, v[6:7], off offset:1024
	global_load_ushort v83, v[6:7], off offset:2304
	global_load_ushort v80, v[6:7], off offset:3584
	global_load_ushort v86, v[8:9], off offset:1024
	global_load_ushort v84, v[8:9], off offset:2304
	global_load_ushort v79, v[8:9], off offset:3584
	v_add_co_u32_e32 v6, vcc, s42, v4
	s_addc_u32 s38, s38, 0
	s_nop 0
	v_addc_co_u32_e32 v7, vcc, 0, v5, vcc
	v_or_b32_e32 v10, s39, v0
	v_mov_b32_e32 v11, s38
	v_add_co_u32_e32 v8, vcc, s42, v2
	v_lshlrev_b64 v[10:11], 1, v[10:11]
	s_nop 0
	v_addc_co_u32_e32 v9, vcc, 0, v3, vcc
	v_lshl_add_u64 v[12:13], s[50:51], 0, v[10:11]
	v_lshl_add_u64 v[10:11], s[52:53], 0, v[10:11]
	s_movk_i32 s38, 0x3000
	global_load_ushort v78, v[12:13], off
	global_load_ushort v77, v[10:11], off
	global_load_ushort v82, v[6:7], off offset:768
	global_load_ushort v76, v[6:7], off offset:3328
	global_load_ushort v81, v[8:9], off offset:768
	global_load_ushort v75, v[8:9], off offset:3328
	v_add_co_u32_e32 v6, vcc, s38, v4
	s_mul_i32 s7, s40, 10
	s_nop 0
	v_addc_co_u32_e32 v7, vcc, 0, v5, vcc
	v_add_co_u32_e32 v8, vcc, s38, v2
	s_add_i32 s7, s7, s37
	s_nop 0
	v_addc_co_u32_e32 v9, vcc, 0, v3, vcc
	v_add_co_u32_e32 v4, vcc, s47, v4
	v_ashrrev_i32_e32 v20, 3, v53
	s_nop 0
	v_addc_co_u32_e32 v5, vcc, 0, v5, vcc
	v_add_co_u32_e32 v2, vcc, s47, v2
	v_lshlrev_b32_e32 v0, 3, v53
	s_lshl_b32 s66, s7, 6
	s_lshl_b32 s7, s41, 7
	v_addc_co_u32_e32 v3, vcc, 0, v3, vcc
	v_and_b32_e32 v61, 56, v0
	v_ashrrev_i32_e32 v21, 31, v20
	s_add_u32 s38, s54, s7
	global_load_ushort v73, v[6:7], off offset:512
	global_load_ushort v71, v[6:7], off offset:1792
	global_load_ushort v70, v[6:7], off offset:3072
	global_load_ushort v74, v[8:9], off offset:512
	global_load_ushort v72, v[8:9], off offset:1792
	global_load_ushort v69, v[8:9], off offset:3072
	global_load_ushort v67, v[4:5], off offset:256
	global_load_ushort v64, v[4:5], off offset:1536
	global_load_ushort v63, v[4:5], off offset:2816
	global_load_ushort v68, v[2:3], off offset:256
	global_load_ushort v65, v[2:3], off offset:1536
	global_load_ushort v62, v[2:3], off offset:2816
	v_lshl_add_u64 v[2:3], v[20:21], 0, s[66:67]
	s_addc_u32 s39, s55, 0
	v_lshlrev_b32_e32 v0, 1, v61
	s_or_b32 s7, s66, s41
	v_lshl_add_u64 v[4:5], s[38:39], 0, v[0:1]
	s_lshl_b32 s7, s7, 13
	v_lshlrev_b64 v[2:3], 13, v[2:3]
	s_add_u32 s38, s24, s7
	v_lshl_add_u64 v[10:11], v[4:5], 0, v[2:3]
	s_mov_b32 s7, 0x40000
	s_addc_u32 s39, s25, 0
	global_load_dwordx4 v[2:5], v[10:11], off
	v_add_co_u32_e32 v10, vcc, s7, v10
	s_lshl_b32 s7, s37, 8
	v_lshl_add_u64 v[14:15], s[38:39], 0, v[0:1]
	s_add_u32 s38, s89, s7
	s_addc_u32 s39, s90, 0
	s_add_u32 s66, s38, 0xfffffa00
	s_addc_u32 s73, s39, -1
	s_add_u32 s7, s20, s7
	s_addc_u32 s74, s21, 0
	s_cmp_lt_u32 s37, 6
	s_cselect_b64 s[38:39], -1, 0
	v_lshlrev_b32_e32 v16, 6, v20
	v_bfe_u32 v66, v53, 4, 2
	s_and_b64 s[42:43], s[38:39], exec
	v_ashrrev_i32_e32 v17, 31, v16
	s_cselect_b32 s43, s74, s73
	s_cselect_b32 s42, s7, s66
	v_lshlrev_b32_e32 v59, 2, v66
	s_lshl_b32 s7, s37, 7
	v_and_b32_e32 v54, 15, v53
	v_lshl_add_u64 v[6:7], v[16:17], 1, v[14:15]
	v_add_u32_e32 v16, 0x800, v16
	v_or_b32_e32 v18, s72, v59
	s_add_u32 s72, s56, s7
	v_ashrrev_i32_e32 v17, 31, v16
	s_addc_u32 s73, s57, 0
	v_lshlrev_b32_e32 v0, 1, v54
	v_addc_co_u32_e32 v11, vcc, 0, v11, vcc
	v_lshl_add_u64 v[14:15], v[16:17], 1, v[14:15]
	v_lshl_add_u64 v[22:23], s[72:73], 0, v[0:1]
	v_lshlrev_b32_e32 v19, 2, v54
	s_movk_i32 s7, 0x500
	global_load_dwordx4 v[6:9], v[6:7], off nt
	v_mad_i64_i32 v[22:23], s[72:73], v18, s7, v[22:23]
	global_load_dwordx4 v[10:13], v[10:11], off
	v_mov_b32_e32 v99, v154
	global_load_dwordx4 v[14:17], v[14:15], off nt
	s_nop 0
	global_load_dword v40, v19, s[42:43]
	global_load_dword v39, v19, s[42:43] offset:64
	global_load_dword v38, v19, s[42:43] offset:128
	global_load_dword v21, v19, s[42:43] offset:192
	global_load_ushort v58, v[22:23], off
	global_load_ushort v52, v[22:23], off offset:1280
	global_load_ushort v55, v[22:23], off offset:32
	global_load_ushort v51, v[22:23], off offset:1312
	global_load_ushort v56, v[22:23], off offset:64
	global_load_ushort v50, v[22:23], off offset:1344
	global_load_ushort v49, v[22:23], off offset:1376
	global_load_ushort v57, v[22:23], off offset:96
	global_load_ushort v48, v[22:23], off offset:2560
	global_load_ushort v44, v[22:23], off offset:3840
	global_load_ushort v45, v[22:23], off offset:2592
	global_load_ushort v43, v[22:23], off offset:3872
	global_load_ushort v46, v[22:23], off offset:2624
	global_load_ushort v42, v[22:23], off offset:3904
	global_load_ushort v41, v[22:23], off offset:3936
	global_load_ushort v47, v[22:23], off offset:2656
	v_mov_b32_e32 v19, s6
	v_readfirstlane_b32 s43, v99
	s_ashr_i32 s42, s43, 6
	s_cmp_gt_u32 s37, 5
	s_mov_b64 s[6:7], -1
	s_cbranch_scc0 .LBB0_184
	s_lshl_b32 s6, s40, 18
	s_add_u32 s6, s26, s6
	s_addc_u32 s7, s27, 0
	s_lshl_b32 s40, s41, 12
	s_add_u32 s6, s6, s40
	v_lshlrev_b32_e32 v22, 2, v99
	s_addc_u32 s7, s7, 0
	v_ashrrev_i32_e32 v23, 31, v22
	v_and_b32_e32 v28, 63, v99
	v_lshl_add_u64 v[22:23], v[22:23], 2, s[6:7]
	s_add_i32 s6, s34, 0xfffffe80
	global_load_dwordx4 v[106:109], v[22:23], off
	v_or_b32_e32 v22, s6, v28
	v_mov_b32_e32 v23, v1
	v_lshlrev_b64 v[26:27], 2, v[22:23]
	v_lshl_add_u64 v[30:31], s[28:29], 0, v[26:27]
	s_movk_i32 s6, 0x2000
	v_add_co_u32_e32 v110, vcc, s6, v30
	s_movk_i32 s6, 0x3000
	s_nop 0
	v_addc_co_u32_e32 v111, vcc, 0, v31, vcc
	v_add_co_u32_e32 v34, vcc, s6, v30
	global_load_dword v22, v[110:111], off offset:2048
	global_load_dword v23, v[110:111], off offset:3072
	v_addc_co_u32_e32 v35, vcc, 0, v31, vcc
	global_load_dword v32, v[30:31], off
	global_load_dword v24, v[34:35], off
	v_lshl_add_u64 v[26:27], s[30:31], 0, v[26:27]
	global_load_dword v29, v[26:27], off
	global_load_dword v25, v[34:35], off offset:1024
	s_nop 0
	global_load_dword v26, v[34:35], off offset:2048
	global_load_dword v27, v[34:35], off offset:3072
	global_load_dword v95, v[30:31], off offset:1024
	global_load_dword v96, v[30:31], off offset:2048
	global_load_dword v97, v[30:31], off offset:3072
	global_load_dword v37, v[110:111], off offset:-4096
	v_add_co_u32_e32 v30, vcc, s88, v30
	s_lshl_b32 s6, s42, 10
	s_nop 0
	v_addc_co_u32_e32 v31, vcc, 0, v31, vcc
	global_load_dword v34, v[30:31], off offset:1024
	global_load_dword v35, v[30:31], off offset:2048
	global_load_dword v36, v[30:31], off offset:3072
	s_nop 0
	global_load_dword v30, v[110:111], off
	global_load_dword v31, v[110:111], off offset:1024
	v_lshlrev_b32_e32 v99, 4, v99
	v_mov_b32_e32 v33, s6
	s_and_b32 s6, s43, 0x3fffffc0
	s_cmp_gt_i32 s42, 0
	s_waitcnt vmcnt(17)
	ds_write_b128 v99, v[106:109] offset:55296
	s_waitcnt lgkmcnt(0)
	s_barrier
	ds_read_b128 v[106:109], v33 offset:55296
	ds_read_b128 v[110:113], v33 offset:55312
	ds_read_b128 v[114:117], v33 offset:55328
	ds_read_b128 v[118:121], v33 offset:55344
	ds_read_b128 v[122:125], v33 offset:55360
	ds_read_b128 v[126:129], v33 offset:55376
	ds_read_b128 v[130:133], v33 offset:55392
	ds_read_b128 v[134:137], v33 offset:55408
	s_waitcnt vmcnt(15) lgkmcnt(5)
	v_pk_mul_f32 v[116:117], v[22:23], v[116:117]
	s_waitcnt vmcnt(9) lgkmcnt(4)
	v_pk_mul_f32 v[120:121], v[26:27], v[120:121]
	v_fma_f32 v99, v32, v106, v29
	s_waitcnt vmcnt(8)
	v_fmac_f32_e32 v99, v95, v107
	s_waitcnt vmcnt(7)
	v_fmac_f32_e32 v99, v96, v108
	s_waitcnt vmcnt(6)
	v_fmac_f32_e32 v99, v97, v109
	s_waitcnt vmcnt(5)
	v_fmac_f32_e32 v99, v37, v110
	s_waitcnt lgkmcnt(3)
	v_fma_f32 v101, v32, v122, v29
	s_waitcnt vmcnt(4)
	v_fmac_f32_e32 v99, v34, v111
	v_fmac_f32_e32 v101, v95, v123
	s_waitcnt vmcnt(3)
	v_fmac_f32_e32 v99, v35, v112
	v_fmac_f32_e32 v101, v96, v124
	s_waitcnt vmcnt(2)
	v_fmac_f32_e32 v99, v36, v113
	v_fmac_f32_e32 v101, v97, v125
	s_waitcnt vmcnt(1)
	v_fmac_f32_e32 v99, v30, v114
	s_waitcnt lgkmcnt(2)
	v_fmac_f32_e32 v101, v37, v126
	s_waitcnt vmcnt(0)
	v_fmac_f32_e32 v99, v31, v115
	v_fmac_f32_e32 v101, v34, v127
	v_add_f32_e32 v99, v99, v116
	v_pk_mul_f32 v[118:119], v[24:25], v[118:119]
	v_fmac_f32_e32 v101, v35, v128
	v_add_f32_e32 v99, v99, v117
	v_fmac_f32_e32 v101, v36, v129
	v_add_f32_e32 v99, v99, v118
	s_waitcnt lgkmcnt(1)
	v_fmac_f32_e32 v101, v30, v130
	v_add_f32_e32 v99, v99, v119
	v_pk_mul_f32 v[132:133], v[22:23], v[132:133]
	v_fmac_f32_e32 v101, v31, v131
	v_add_f32_e32 v99, v99, v120
	v_add_f32_e32 v101, v101, v132
	v_add_f32_e32 v99, v99, v121
	s_waitcnt lgkmcnt(0)
	v_pk_mul_f32 v[134:135], v[24:25], v[134:135]
	v_add_f32_e32 v101, v101, v133
	v_mul_f32_e64 v103, |v99|, s46
	v_add_f32_e32 v101, v101, v134
	v_exp_f32_e32 v103, v103
	v_pk_mul_f32 v[136:137], v[26:27], v[136:137]
	v_add_f32_e32 v101, v101, v135
	v_add_f32_e32 v101, v101, v136
	v_add_f32_e32 v101, v101, v137
	v_mul_f32_e64 v105, |v101|, s46
	v_add_f32_e32 v103, 1.0, v103
	v_exp_f32_e32 v105, v105
	v_cmp_gt_f32_e32 vcc, s84, v103
	ds_read_b128 v[106:109], v33 offset:55424
	v_max_f32_e64 v99, -v99, 0
	v_cndmask_b32_e64 v110, 0, 32, vcc
	v_ldexp_f32 v103, v103, v110
	v_log_f32_e32 v103, v103
	v_add_f32_e32 v105, 1.0, v105
	v_cmp_gt_f32_e64 s[40:41], s84, v105
	v_cndmask_b32_e32 v110, 0, v161, vcc
	v_cmp_lt_f32_e64 vcc, |v103|, s45
	v_cndmask_b32_e64 v111, 0, 32, s[40:41]
	v_ldexp_f32 v105, v105, v111
	v_mul_f32_e32 v111, 0x3f317217, v103
	v_log_f32_e32 v105, v105
	v_fma_f32 v111, v103, s44, -v111
	v_fmac_f32_e32 v111, 0x3377d1cf, v103
	v_fmac_f32_e32 v111, 0x3f317217, v103
	v_cndmask_b32_e32 v103, v103, v111, vcc
	v_mul_f32_e32 v112, 0x3f317217, v105
	v_sub_f32_e32 v103, v103, v110
	v_add_f32_e32 v99, v99, v103
	v_fma_f32 v103, v105, s44, -v112
	ds_read_b128 v[110:113], v33 offset:55440
	s_waitcnt lgkmcnt(1)
	v_fma_f32 v114, v32, v106, v29
	v_fmac_f32_e32 v114, v95, v107
	v_fmac_f32_e32 v114, v96, v108
	v_fmac_f32_e32 v114, v97, v109
	s_waitcnt lgkmcnt(0)
	v_fmac_f32_e32 v114, v37, v110
	ds_read_b128 v[106:109], v33 offset:55456
	v_fmac_f32_e32 v114, v34, v111
	v_fmac_f32_e32 v114, v35, v112
	v_fmac_f32_e32 v114, v36, v113
	ds_read_b128 v[110:113], v33 offset:55472
	s_waitcnt lgkmcnt(1)
	v_fmac_f32_e32 v114, v30, v106
	v_fmac_f32_e32 v114, v31, v107
	v_pk_mul_f32 v[106:107], v[22:23], v[108:109]
	v_fmac_f32_e32 v103, 0x3377d1cf, v105
	v_add_f32_e32 v106, v114, v106
	v_add_f32_e32 v108, v106, v107
	s_waitcnt lgkmcnt(0)
	v_pk_mul_f32 v[106:107], v[24:25], v[110:111]
	v_fmac_f32_e32 v103, 0x3f317217, v105
	v_add_f32_e32 v106, v108, v106
	v_add_f32_e32 v108, v106, v107
	v_pk_mul_f32 v[106:107], v[26:27], v[112:113]
	v_cmp_lt_f32_e64 vcc, |v105|, s45
	v_add_f32_e32 v106, v108, v106
	v_add_f32_e32 v106, v106, v107
	v_mul_f32_e64 v107, |v106|, s46
	v_exp_f32_e32 v107, v107
	v_cndmask_b32_e32 v103, v105, v103, vcc
	v_cndmask_b32_e64 v105, 0, v161, s[40:41]
	v_max_f32_e64 v101, -v101, 0
	v_add_f32_e32 v107, 1.0, v107
	v_cmp_gt_f32_e32 vcc, s84, v107
	v_sub_f32_e32 v103, v103, v105
	v_add_f32_e32 v101, v101, v103
	v_cndmask_b32_e64 v108, 0, 32, vcc
	v_ldexp_f32 v107, v107, v108
	v_log_f32_e32 v114, v107
	v_max_f32_e64 v103, -v106, 0
	ds_read_b128 v[106:109], v33 offset:55488
	ds_read_b128 v[110:113], v33 offset:55504
	v_mul_f32_e32 v105, 0x3f317217, v114
	v_fma_f32 v105, v114, s44, -v105
	v_fmac_f32_e32 v105, 0x3377d1cf, v114
	s_waitcnt lgkmcnt(1)
	v_fma_f32 v115, v32, v106, v29
	v_fmac_f32_e32 v115, v95, v107
	v_fmac_f32_e32 v115, v96, v108
	v_fmac_f32_e32 v115, v97, v109
	s_waitcnt lgkmcnt(0)
	v_fmac_f32_e32 v115, v37, v110
	ds_read_b128 v[106:109], v33 offset:55520
	v_fmac_f32_e32 v115, v34, v111
	v_fmac_f32_e32 v115, v35, v112
	v_fmac_f32_e32 v115, v36, v113
	ds_read_b128 v[110:113], v33 offset:55536
	s_waitcnt lgkmcnt(1)
	v_fmac_f32_e32 v115, v30, v106
	v_fmac_f32_e32 v115, v31, v107
	v_pk_mul_f32 v[106:107], v[22:23], v[108:109]
	v_fmac_f32_e32 v105, 0x3f317217, v114
	v_add_f32_e32 v106, v115, v106
	v_add_f32_e32 v108, v106, v107
	s_waitcnt lgkmcnt(0)
	v_pk_mul_f32 v[106:107], v[24:25], v[110:111]
	v_cmp_lt_f32_e64 s[40:41], |v114|, s45
	v_add_f32_e32 v106, v108, v106
	v_add_f32_e32 v108, v106, v107
	v_pk_mul_f32 v[106:107], v[26:27], v[112:113]
	v_cndmask_b32_e64 v105, v114, v105, s[40:41]
	v_add_f32_e32 v106, v108, v106
	v_add_f32_e32 v106, v106, v107
	v_mul_f32_e64 v107, |v106|, s46
	v_exp_f32_e32 v107, v107
	v_cndmask_b32_e32 v108, 0, v161, vcc
	v_sub_f32_e32 v105, v105, v108
	v_add_f32_e32 v103, v103, v105
	v_add_f32_e32 v107, 1.0, v107
	v_cmp_gt_f32_e32 vcc, s84, v107
	v_max_f32_e64 v105, -v106, 0
	s_nop 0
	v_cndmask_b32_e64 v109, 0, 32, vcc
	v_ldexp_f32 v107, v107, v109
	v_log_f32_e32 v114, v107
	ds_read_b128 v[106:109], v33 offset:55552
	v_mul_f32_e32 v110, 0x3f317217, v114
	v_fma_f32 v115, v114, s44, -v110
	ds_read_b128 v[110:113], v33 offset:55568
	s_waitcnt lgkmcnt(1)
	v_fma_f32 v116, v32, v106, v29
	v_fmac_f32_e32 v116, v95, v107
	v_fmac_f32_e32 v116, v96, v108
	v_fmac_f32_e32 v116, v97, v109
	s_waitcnt lgkmcnt(0)
	v_fmac_f32_e32 v116, v37, v110
	ds_read_b128 v[106:109], v33 offset:55584
	v_fmac_f32_e32 v116, v34, v111
	v_fmac_f32_e32 v116, v35, v112
	v_fmac_f32_e32 v116, v36, v113
	ds_read_b128 v[110:113], v33 offset:55600
	s_waitcnt lgkmcnt(1)
	v_fmac_f32_e32 v116, v30, v106
	v_fmac_f32_e32 v116, v31, v107
	v_pk_mul_f32 v[106:107], v[22:23], v[108:109]
	v_fmac_f32_e32 v115, 0x3377d1cf, v114
	v_add_f32_e32 v106, v116, v106
	v_add_f32_e32 v108, v106, v107
	s_waitcnt lgkmcnt(0)
	v_pk_mul_f32 v[106:107], v[24:25], v[110:111]
	v_cndmask_b32_e32 v109, 0, v161, vcc
	v_add_f32_e32 v106, v108, v106
	v_add_f32_e32 v108, v106, v107
	v_pk_mul_f32 v[106:107], v[26:27], v[112:113]
	v_fmac_f32_e32 v115, 0x3f317217, v114
	v_add_f32_e32 v106, v108, v106
	v_add_f32_e32 v106, v106, v107
	v_mul_f32_e64 v107, |v106|, s46
	v_exp_f32_e32 v107, v107
	v_cmp_lt_f32_e64 s[40:41], |v114|, s45
	v_add_f32_e32 v107, 1.0, v107
	v_cmp_gt_f32_e32 vcc, s84, v107
	v_cndmask_b32_e64 v108, v114, v115, s[40:41]
	v_max_f32_e64 v115, -v106, 0
	v_cndmask_b32_e64 v110, 0, 32, vcc
	v_ldexp_f32 v107, v107, v110
	v_log_f32_e32 v114, v107
	v_sub_f32_e32 v107, v108, v109
	v_add_f32_e32 v105, v105, v107
	ds_read_b128 v[106:109], v33 offset:55616
	v_mul_f32_e32 v110, 0x3f317217, v114
	v_fma_f32 v116, v114, s44, -v110
	ds_read_b128 v[110:113], v33 offset:55632
	v_fmac_f32_e32 v116, 0x3377d1cf, v114
	s_waitcnt lgkmcnt(1)
	v_fma_f32 v117, v32, v106, v29
	v_fmac_f32_e32 v117, v95, v107
	v_fmac_f32_e32 v117, v96, v108
	v_fmac_f32_e32 v117, v97, v109
	s_waitcnt lgkmcnt(0)
	v_fmac_f32_e32 v117, v37, v110
	ds_read_b128 v[106:109], v33 offset:55648
	v_fmac_f32_e32 v117, v34, v111
	v_fmac_f32_e32 v117, v35, v112
	v_fmac_f32_e32 v117, v36, v113
	ds_read_b128 v[110:113], v33 offset:55664
	s_waitcnt lgkmcnt(1)
	v_fmac_f32_e32 v117, v30, v106
	v_fmac_f32_e32 v117, v31, v107
	v_pk_mul_f32 v[106:107], v[22:23], v[108:109]
	v_cndmask_b32_e32 v109, 0, v161, vcc
	v_add_f32_e32 v106, v117, v106
	v_add_f32_e32 v108, v106, v107
	s_waitcnt lgkmcnt(0)
	v_pk_mul_f32 v[106:107], v[24:25], v[110:111]
	v_fmac_f32_e32 v116, 0x3f317217, v114
	v_add_f32_e32 v106, v108, v106
	v_add_f32_e32 v108, v106, v107
	v_pk_mul_f32 v[106:107], v[26:27], v[112:113]
	v_cmp_lt_f32_e64 s[40:41], |v114|, s45
	v_add_f32_e32 v106, v108, v106
	v_add_f32_e32 v107, v106, v107
	v_mul_f32_e64 v106, |v107|, s46
	v_exp_f32_e32 v106, v106
	v_cndmask_b32_e64 v108, v114, v116, s[40:41]
	v_max_f32_e64 v107, -v107, 0
	v_add_f32_e32 v106, 1.0, v106
	v_cmp_gt_f32_e32 vcc, s84, v106
	s_nop 1
	v_cndmask_b32_e64 v110, 0, 32, vcc
	v_ldexp_f32 v106, v106, v110
	v_log_f32_e32 v116, v106
	v_sub_f32_e32 v106, v108, v109
	ds_read_b128 v[108:111], v33 offset:55680
	v_add_f32_e32 v106, v115, v106
	v_mul_f32_e32 v112, 0x3f317217, v116
	v_fma_f32 v117, v116, s44, -v112
	ds_read_b128 v[112:115], v33 offset:55696
	s_waitcnt lgkmcnt(1)
	v_fma_f32 v118, v32, v108, v29
	v_fmac_f32_e32 v118, v95, v109
	v_fmac_f32_e32 v118, v96, v110
	v_fmac_f32_e32 v118, v97, v111
	s_waitcnt lgkmcnt(0)
	v_fmac_f32_e32 v118, v37, v112
	ds_read_b128 v[108:111], v33 offset:55712
	v_fmac_f32_e32 v118, v34, v113
	v_fmac_f32_e32 v118, v35, v114
	v_fmac_f32_e32 v118, v36, v115
	ds_read_b128 v[112:115], v33 offset:55728
	s_waitcnt lgkmcnt(1)
	v_fmac_f32_e32 v118, v30, v108
	v_fmac_f32_e32 v118, v31, v109
	v_pk_mul_f32 v[108:109], v[22:23], v[110:111]
	v_fmac_f32_e32 v117, 0x3377d1cf, v116
	v_add_f32_e32 v108, v118, v108
	v_add_f32_e32 v110, v108, v109
	s_waitcnt lgkmcnt(0)
	v_pk_mul_f32 v[108:109], v[24:25], v[112:113]
	v_cndmask_b32_e32 v111, 0, v161, vcc
	v_add_f32_e32 v108, v110, v108
	v_add_f32_e32 v110, v108, v109
	v_pk_mul_f32 v[108:109], v[26:27], v[114:115]
	v_fmac_f32_e32 v117, 0x3f317217, v116
	v_add_f32_e32 v108, v110, v108
	v_add_f32_e32 v108, v108, v109
	v_mul_f32_e64 v109, |v108|, s46
	v_exp_f32_e32 v109, v109
	v_cmp_lt_f32_e64 s[40:41], |v116|, s45
	v_add_f32_e32 v109, 1.0, v109
	v_cmp_gt_f32_e32 vcc, s84, v109
	v_cndmask_b32_e64 v110, v116, v117, s[40:41]
	v_max_f32_e64 v117, -v108, 0
	v_cndmask_b32_e64 v112, 0, 32, vcc
	v_ldexp_f32 v109, v109, v112
	v_log_f32_e32 v116, v109
	v_sub_f32_e32 v109, v110, v111
	v_add_f32_e32 v107, v107, v109
	ds_read_b128 v[108:111], v33 offset:55744
	v_mul_f32_e32 v112, 0x3f317217, v116
	v_fma_f32 v118, v116, s44, -v112
	ds_read_b128 v[112:115], v33 offset:55760
	v_fmac_f32_e32 v118, 0x3377d1cf, v116
	s_waitcnt lgkmcnt(1)
	v_fma_f32 v119, v32, v108, v29
	v_fmac_f32_e32 v119, v95, v109
	v_fmac_f32_e32 v119, v96, v110
	v_fmac_f32_e32 v119, v97, v111
	s_waitcnt lgkmcnt(0)
	v_fmac_f32_e32 v119, v37, v112
	ds_read_b128 v[108:111], v33 offset:55776
	v_fmac_f32_e32 v119, v34, v113
	v_fmac_f32_e32 v119, v35, v114
	v_fmac_f32_e32 v119, v36, v115
	ds_read_b128 v[112:115], v33 offset:55792
	s_waitcnt lgkmcnt(1)
	v_fmac_f32_e32 v119, v30, v108
	v_fmac_f32_e32 v119, v31, v109
	v_pk_mul_f32 v[108:109], v[22:23], v[110:111]
	v_cndmask_b32_e32 v111, 0, v161, vcc
	v_add_f32_e32 v108, v119, v108
	v_add_f32_e32 v110, v108, v109
	s_waitcnt lgkmcnt(0)
	v_pk_mul_f32 v[108:109], v[24:25], v[112:113]
	v_fmac_f32_e32 v118, 0x3f317217, v116
	v_add_f32_e32 v108, v110, v108
	v_add_f32_e32 v110, v108, v109
	v_pk_mul_f32 v[108:109], v[26:27], v[114:115]
	v_cmp_lt_f32_e64 s[40:41], |v116|, s45
	v_add_f32_e32 v108, v110, v108
	v_add_f32_e32 v109, v108, v109
	v_mul_f32_e64 v108, |v109|, s46
	v_exp_f32_e32 v108, v108
	v_cndmask_b32_e64 v110, v116, v118, s[40:41]
	v_max_f32_e64 v109, -v109, 0
	v_add_f32_e32 v108, 1.0, v108
	v_cmp_gt_f32_e32 vcc, s84, v108
	s_nop 1
	v_cndmask_b32_e64 v112, 0, 32, vcc
	v_ldexp_f32 v108, v108, v112
	v_log_f32_e32 v118, v108
	v_sub_f32_e32 v108, v110, v111
	ds_read_b128 v[110:113], v33 offset:55808
	v_add_f32_e32 v108, v117, v108
	v_mul_f32_e32 v114, 0x3f317217, v118
	v_fma_f32 v119, v118, s44, -v114
	ds_read_b128 v[114:117], v33 offset:55824
	s_waitcnt lgkmcnt(1)
	v_fma_f32 v120, v32, v110, v29
	v_fmac_f32_e32 v120, v95, v111
	v_fmac_f32_e32 v120, v96, v112
	v_fmac_f32_e32 v120, v97, v113
	s_waitcnt lgkmcnt(0)
	v_fmac_f32_e32 v120, v37, v114
	ds_read_b128 v[110:113], v33 offset:55840
	v_fmac_f32_e32 v120, v34, v115
	v_fmac_f32_e32 v120, v35, v116
	v_fmac_f32_e32 v120, v36, v117
	ds_read_b128 v[114:117], v33 offset:55856
	s_waitcnt lgkmcnt(1)
	v_fmac_f32_e32 v120, v30, v110
	v_fmac_f32_e32 v120, v31, v111
	v_pk_mul_f32 v[110:111], v[22:23], v[112:113]
	v_fmac_f32_e32 v119, 0x3377d1cf, v118
	v_add_f32_e32 v110, v120, v110
	v_add_f32_e32 v112, v110, v111
	s_waitcnt lgkmcnt(0)
	v_pk_mul_f32 v[110:111], v[24:25], v[114:115]
	v_cndmask_b32_e32 v113, 0, v161, vcc
	v_add_f32_e32 v110, v112, v110
	v_add_f32_e32 v112, v110, v111
	v_pk_mul_f32 v[110:111], v[26:27], v[116:117]
	v_fmac_f32_e32 v119, 0x3f317217, v118
	v_add_f32_e32 v110, v112, v110
	v_add_f32_e32 v110, v110, v111
	v_mul_f32_e64 v111, |v110|, s46
	v_exp_f32_e32 v111, v111
	v_cmp_lt_f32_e64 s[40:41], |v118|, s45
	v_add_f32_e32 v111, 1.0, v111
	v_cmp_gt_f32_e32 vcc, s84, v111
	v_cndmask_b32_e64 v112, v118, v119, s[40:41]
	v_max_f32_e64 v119, -v110, 0
	v_cndmask_b32_e64 v114, 0, 32, vcc
	v_ldexp_f32 v111, v111, v114
	v_log_f32_e32 v118, v111
	v_sub_f32_e32 v111, v112, v113
	v_add_f32_e32 v109, v109, v111
	ds_read_b128 v[110:113], v33 offset:55872
	v_mul_f32_e32 v114, 0x3f317217, v118
	v_fma_f32 v120, v118, s44, -v114
	ds_read_b128 v[114:117], v33 offset:55888
	v_fmac_f32_e32 v120, 0x3377d1cf, v118
	s_waitcnt lgkmcnt(1)
	v_fma_f32 v121, v32, v110, v29
	v_fmac_f32_e32 v121, v95, v111
	v_fmac_f32_e32 v121, v96, v112
	v_fmac_f32_e32 v121, v97, v113
	s_waitcnt lgkmcnt(0)
	v_fmac_f32_e32 v121, v37, v114
	ds_read_b128 v[110:113], v33 offset:55904
	v_fmac_f32_e32 v121, v34, v115
	v_fmac_f32_e32 v121, v35, v116
	v_fmac_f32_e32 v121, v36, v117
	ds_read_b128 v[114:117], v33 offset:55920
	s_waitcnt lgkmcnt(1)
	v_fmac_f32_e32 v121, v30, v110
	v_fmac_f32_e32 v121, v31, v111
	v_pk_mul_f32 v[110:111], v[22:23], v[112:113]
	v_cndmask_b32_e32 v113, 0, v161, vcc
	v_add_f32_e32 v110, v121, v110
	v_add_f32_e32 v112, v110, v111
	s_waitcnt lgkmcnt(0)
	v_pk_mul_f32 v[110:111], v[24:25], v[114:115]
	v_fmac_f32_e32 v120, 0x3f317217, v118
	v_add_f32_e32 v110, v112, v110
	v_add_f32_e32 v112, v110, v111
	v_pk_mul_f32 v[110:111], v[26:27], v[116:117]
	v_cmp_lt_f32_e64 s[40:41], |v118|, s45
	v_add_f32_e32 v110, v112, v110
	v_add_f32_e32 v110, v110, v111
	v_mul_f32_e64 v111, |v110|, s46
	v_exp_f32_e32 v111, v111
	v_cndmask_b32_e64 v112, v118, v120, s[40:41]
	v_max_f32_e64 v120, -v110, 0
	v_add_f32_e32 v111, 1.0, v111
	v_cmp_gt_f32_e32 vcc, s84, v111
	s_nop 1
	v_cndmask_b32_e64 v114, 0, 32, vcc
	v_ldexp_f32 v111, v111, v114
	v_log_f32_e32 v118, v111
	v_sub_f32_e32 v111, v112, v113
	v_add_f32_e32 v119, v119, v111
	ds_read_b128 v[110:113], v33 offset:55936
	v_mul_f32_e32 v114, 0x3f317217, v118
	v_fma_f32 v121, v118, s44, -v114
	ds_read_b128 v[114:117], v33 offset:55952
	v_fmac_f32_e32 v121, 0x3377d1cf, v118
	s_waitcnt lgkmcnt(1)
	v_fma_f32 v122, v32, v110, v29
	v_fmac_f32_e32 v122, v95, v111
	v_fmac_f32_e32 v122, v96, v112
	v_fmac_f32_e32 v122, v97, v113
	s_waitcnt lgkmcnt(0)
	v_fmac_f32_e32 v122, v37, v114
	ds_read_b128 v[110:113], v33 offset:55968
	v_fmac_f32_e32 v122, v34, v115
	v_fmac_f32_e32 v122, v35, v116
	v_fmac_f32_e32 v122, v36, v117
	ds_read_b128 v[114:117], v33 offset:55984
	s_waitcnt lgkmcnt(1)
	v_fmac_f32_e32 v122, v30, v110
	v_fmac_f32_e32 v122, v31, v111
	v_pk_mul_f32 v[110:111], v[22:23], v[112:113]
	v_cndmask_b32_e32 v113, 0, v161, vcc
	v_add_f32_e32 v110, v122, v110
	v_add_f32_e32 v112, v110, v111
	s_waitcnt lgkmcnt(0)
	v_pk_mul_f32 v[110:111], v[24:25], v[114:115]
	v_fmac_f32_e32 v121, 0x3f317217, v118
	v_add_f32_e32 v110, v112, v110
	v_add_f32_e32 v112, v110, v111
	v_pk_mul_f32 v[110:111], v[26:27], v[116:117]
	v_cmp_lt_f32_e64 s[40:41], |v118|, s45
	v_add_f32_e32 v110, v112, v110
	v_add_f32_e32 v110, v110, v111
	v_mul_f32_e64 v111, |v110|, s46
	v_exp_f32_e32 v111, v111
	v_cndmask_b32_e64 v112, v118, v121, s[40:41]
	v_max_f32_e64 v121, -v110, 0
	v_add_f32_e32 v111, 1.0, v111
	v_cmp_gt_f32_e32 vcc, s84, v111
	s_nop 1
	v_cndmask_b32_e64 v114, 0, 32, vcc
	v_ldexp_f32 v111, v111, v114
	v_log_f32_e32 v118, v111
	v_sub_f32_e32 v111, v112, v113
	v_add_f32_e32 v120, v120, v111
	ds_read_b128 v[110:113], v33 offset:56000
	v_mul_f32_e32 v114, 0x3f317217, v118
	v_fma_f32 v122, v118, s44, -v114
	ds_read_b128 v[114:117], v33 offset:56016
	v_fmac_f32_e32 v122, 0x3377d1cf, v118
	s_waitcnt lgkmcnt(1)
	v_fma_f32 v123, v32, v110, v29
	v_fmac_f32_e32 v123, v95, v111
	v_fmac_f32_e32 v123, v96, v112
	v_fmac_f32_e32 v123, v97, v113
	s_waitcnt lgkmcnt(0)
	v_fmac_f32_e32 v123, v37, v114
	ds_read_b128 v[110:113], v33 offset:56032
	v_fmac_f32_e32 v123, v34, v115
	v_fmac_f32_e32 v123, v35, v116
	v_fmac_f32_e32 v123, v36, v117
	ds_read_b128 v[114:117], v33 offset:56048
	s_waitcnt lgkmcnt(1)
	v_fmac_f32_e32 v123, v30, v110
	v_fmac_f32_e32 v123, v31, v111
	v_pk_mul_f32 v[110:111], v[22:23], v[112:113]
	v_cndmask_b32_e32 v113, 0, v161, vcc
	v_add_f32_e32 v110, v123, v110
	v_add_f32_e32 v112, v110, v111
	s_waitcnt lgkmcnt(0)
	v_pk_mul_f32 v[110:111], v[24:25], v[114:115]
	v_fmac_f32_e32 v122, 0x3f317217, v118
	v_add_f32_e32 v110, v112, v110
	v_add_f32_e32 v112, v110, v111
	v_pk_mul_f32 v[110:111], v[26:27], v[116:117]
	v_cmp_lt_f32_e64 s[40:41], |v118|, s45
	v_add_f32_e32 v110, v112, v110
	v_add_f32_e32 v110, v110, v111
	v_mul_f32_e64 v111, |v110|, s46
	v_exp_f32_e32 v111, v111
	v_cndmask_b32_e64 v112, v118, v122, s[40:41]
	v_max_f32_e64 v122, -v110, 0
	v_add_f32_e32 v111, 1.0, v111
	v_cmp_gt_f32_e32 vcc, s84, v111
	s_nop 1
	v_cndmask_b32_e64 v114, 0, 32, vcc
	v_ldexp_f32 v111, v111, v114
	v_log_f32_e32 v118, v111
	v_sub_f32_e32 v111, v112, v113
	v_add_f32_e32 v121, v121, v111
	ds_read_b128 v[110:113], v33 offset:56064
	v_mul_f32_e32 v114, 0x3f317217, v118
	v_fma_f32 v123, v118, s44, -v114
	ds_read_b128 v[114:117], v33 offset:56080
	v_fmac_f32_e32 v123, 0x3377d1cf, v118
	s_waitcnt lgkmcnt(1)
	v_fma_f32 v124, v32, v110, v29
	v_fmac_f32_e32 v124, v95, v111
	v_fmac_f32_e32 v124, v96, v112
	v_fmac_f32_e32 v124, v97, v113
	s_waitcnt lgkmcnt(0)
	v_fmac_f32_e32 v124, v37, v114
	ds_read_b128 v[110:113], v33 offset:56096
	v_fmac_f32_e32 v124, v34, v115
	v_fmac_f32_e32 v124, v35, v116
	v_fmac_f32_e32 v124, v36, v117
	ds_read_b128 v[114:117], v33 offset:56112
	s_waitcnt lgkmcnt(1)
	v_fmac_f32_e32 v124, v30, v110
	v_fmac_f32_e32 v124, v31, v111
	v_pk_mul_f32 v[110:111], v[22:23], v[112:113]
	v_cndmask_b32_e32 v113, 0, v161, vcc
	v_add_f32_e32 v110, v124, v110
	v_add_f32_e32 v112, v110, v111
	s_waitcnt lgkmcnt(0)
	v_pk_mul_f32 v[110:111], v[24:25], v[114:115]
	v_fmac_f32_e32 v123, 0x3f317217, v118
	v_add_f32_e32 v110, v112, v110
	v_add_f32_e32 v112, v110, v111
	v_pk_mul_f32 v[110:111], v[26:27], v[116:117]
	v_cmp_lt_f32_e64 s[40:41], |v118|, s45
	v_add_f32_e32 v110, v112, v110
	v_add_f32_e32 v110, v110, v111
	v_mul_f32_e64 v111, |v110|, s46
	v_exp_f32_e32 v111, v111
	v_cndmask_b32_e64 v112, v118, v123, s[40:41]
	v_max_f32_e64 v123, -v110, 0
	v_add_f32_e32 v111, 1.0, v111
	v_cmp_gt_f32_e32 vcc, s84, v111
	s_nop 1
	v_cndmask_b32_e64 v114, 0, 32, vcc
	v_ldexp_f32 v111, v111, v114
	v_log_f32_e32 v118, v111
	v_sub_f32_e32 v111, v112, v113
	v_add_f32_e32 v122, v122, v111
	ds_read_b128 v[110:113], v33 offset:56128
	v_mul_f32_e32 v114, 0x3f317217, v118
	v_fma_f32 v124, v118, s44, -v114
	ds_read_b128 v[114:117], v33 offset:56144
	v_fmac_f32_e32 v124, 0x3377d1cf, v118
	s_waitcnt lgkmcnt(1)
	v_fma_f32 v125, v32, v110, v29
	v_fmac_f32_e32 v125, v95, v111
	v_fmac_f32_e32 v125, v96, v112
	v_fmac_f32_e32 v125, v97, v113
	s_waitcnt lgkmcnt(0)
	v_fmac_f32_e32 v125, v37, v114
	ds_read_b128 v[110:113], v33 offset:56160
	v_fmac_f32_e32 v125, v34, v115
	v_fmac_f32_e32 v125, v35, v116
	v_fmac_f32_e32 v125, v36, v117
	ds_read_b128 v[114:117], v33 offset:56176
	s_waitcnt lgkmcnt(1)
	v_fmac_f32_e32 v125, v30, v110
	v_fmac_f32_e32 v125, v31, v111
	v_pk_mul_f32 v[110:111], v[22:23], v[112:113]
	v_cndmask_b32_e32 v113, 0, v161, vcc
	v_add_f32_e32 v110, v125, v110
	v_add_f32_e32 v112, v110, v111
	s_waitcnt lgkmcnt(0)
	v_pk_mul_f32 v[110:111], v[24:25], v[114:115]
	v_fmac_f32_e32 v124, 0x3f317217, v118
	v_add_f32_e32 v110, v112, v110
	v_add_f32_e32 v112, v110, v111
	v_pk_mul_f32 v[110:111], v[26:27], v[116:117]
	v_cmp_lt_f32_e64 s[40:41], |v118|, s45
	v_add_f32_e32 v110, v112, v110
	v_add_f32_e32 v110, v110, v111
	v_mul_f32_e64 v111, |v110|, s46
	v_exp_f32_e32 v111, v111
	v_cndmask_b32_e64 v112, v118, v124, s[40:41]
	v_max_f32_e64 v124, -v110, 0
	v_add_f32_e32 v111, 1.0, v111
	v_cmp_gt_f32_e32 vcc, s84, v111
	s_nop 1
	v_cndmask_b32_e64 v114, 0, 32, vcc
	v_ldexp_f32 v111, v111, v114
	v_log_f32_e32 v118, v111
	v_sub_f32_e32 v111, v112, v113
	v_add_f32_e32 v123, v123, v111
	ds_read_b128 v[110:113], v33 offset:56192
	v_mul_f32_e32 v114, 0x3f317217, v118
	v_fma_f32 v125, v118, s44, -v114
	ds_read_b128 v[114:117], v33 offset:56208
	v_fmac_f32_e32 v125, 0x3377d1cf, v118
	s_waitcnt lgkmcnt(1)
	v_fma_f32 v126, v32, v110, v29
	v_fmac_f32_e32 v126, v95, v111
	v_fmac_f32_e32 v126, v96, v112
	v_fmac_f32_e32 v126, v97, v113
	s_waitcnt lgkmcnt(0)
	v_fmac_f32_e32 v126, v37, v114
	ds_read_b128 v[110:113], v33 offset:56224
	v_fmac_f32_e32 v126, v34, v115
	v_fmac_f32_e32 v126, v35, v116
	v_fmac_f32_e32 v126, v36, v117
	ds_read_b128 v[114:117], v33 offset:56240
	s_waitcnt lgkmcnt(1)
	v_fmac_f32_e32 v126, v30, v110
	v_fmac_f32_e32 v126, v31, v111
	v_pk_mul_f32 v[110:111], v[22:23], v[112:113]
	v_cndmask_b32_e32 v113, 0, v161, vcc
	v_add_f32_e32 v110, v126, v110
	v_add_f32_e32 v112, v110, v111
	s_waitcnt lgkmcnt(0)
	v_pk_mul_f32 v[110:111], v[24:25], v[114:115]
	v_fmac_f32_e32 v125, 0x3f317217, v118
	v_add_f32_e32 v110, v112, v110
	v_add_f32_e32 v112, v110, v111
	v_pk_mul_f32 v[110:111], v[26:27], v[116:117]
	v_cmp_lt_f32_e64 s[40:41], |v118|, s45
	v_add_f32_e32 v110, v112, v110
	v_add_f32_e32 v110, v110, v111
	v_mul_f32_e64 v111, |v110|, s46
	v_exp_f32_e32 v111, v111
	v_cndmask_b32_e64 v112, v118, v125, s[40:41]
	v_max_f32_e64 v125, -v110, 0
	v_add_f32_e32 v111, 1.0, v111
	v_cmp_gt_f32_e32 vcc, s84, v111
	s_nop 1
	v_cndmask_b32_e64 v114, 0, 32, vcc
	v_ldexp_f32 v111, v111, v114
	v_log_f32_e32 v118, v111
	v_sub_f32_e32 v111, v112, v113
	v_add_f32_e32 v124, v124, v111
	ds_read_b128 v[110:113], v33 offset:56256
	v_mul_f32_e32 v114, 0x3f317217, v118
	v_fma_f32 v126, v118, s44, -v114
	ds_read_b128 v[114:117], v33 offset:56272
	v_fmac_f32_e32 v126, 0x3377d1cf, v118
	s_waitcnt lgkmcnt(1)
	v_fmac_f32_e32 v29, v32, v110
	v_fmac_f32_e32 v29, v95, v111
	v_fmac_f32_e32 v29, v96, v112
	v_fmac_f32_e32 v29, v97, v113
	ds_read_b128 v[110:113], v33 offset:56288
	s_waitcnt lgkmcnt(1)
	v_fmac_f32_e32 v29, v37, v114
	v_fmac_f32_e32 v29, v34, v115
	v_fmac_f32_e32 v29, v35, v116
	ds_read_b128 v[32:35], v33 offset:56304
	v_fmac_f32_e32 v29, v36, v117
	s_waitcnt lgkmcnt(1)
	v_fmac_f32_e32 v29, v30, v110
	v_fmac_f32_e32 v29, v31, v111
	v_pk_mul_f32 v[22:23], v[22:23], v[112:113]
	v_lshlrev_b32_e32 v110, 2, v28
	v_add_f32_e32 v22, v29, v22
	v_add_f32_e32 v29, v22, v23
	s_waitcnt lgkmcnt(0)
	v_pk_mul_f32 v[22:23], v[24:25], v[32:33]
	v_lshl_or_b32 v96, s6, 2, v110
	v_add_f32_e32 v22, v29, v22
	v_add_f32_e32 v24, v22, v23
	v_pk_mul_f32 v[22:23], v[26:27], v[34:35]
	s_mov_b32 s6, 0xbd800000
	v_add_f32_e32 v22, v24, v22
	v_add_f32_e32 v22, v22, v23
	v_mul_f32_e64 v23, |v22|, s46
	v_exp_f32_e32 v23, v23
	v_cndmask_b32_e32 v25, 0, v161, vcc
	v_fma_f32 v36, v99, s6, 0
	v_fmamk_f32 v37, v101, 0xbd800000, v36
	v_add_f32_e32 v23, 1.0, v23
	v_cmp_gt_f32_e32 vcc, s84, v23
	v_fmamk_f32 v34, v103, 0xbd800000, v37
	v_fmamk_f32 v35, v105, 0xbd800000, v34
	v_cndmask_b32_e64 v26, 0, 32, vcc
	v_ldexp_f32 v23, v23, v26
	v_log_f32_e32 v23, v23
	v_fmac_f32_e32 v126, 0x3f317217, v118
	v_cmp_lt_f32_e64 s[40:41], |v118|, s45
	v_fmamk_f32 v32, v106, 0xbd800000, v35
	v_fmamk_f32 v33, v107, 0xbd800000, v32
	v_cndmask_b32_e64 v24, v118, v126, s[40:41]
	v_sub_f32_e32 v24, v24, v25
	v_fmamk_f32 v30, v108, 0xbd800000, v33
	v_add_f32_e32 v95, v125, v24
	v_mul_f32_e32 v24, 0x3f317217, v23
	v_fmamk_f32 v31, v109, 0xbd800000, v30
	v_fma_f32 v24, v23, s44, -v24
	v_fmamk_f32 v28, v119, 0xbd800000, v31
	v_fmac_f32_e32 v24, 0x3377d1cf, v23
	v_fmamk_f32 v29, v120, 0xbd800000, v28
	v_fmac_f32_e32 v24, 0x3f317217, v23
	v_cmp_lt_f32_e64 s[40:41], |v23|, s45
	v_fmamk_f32 v26, v121, 0xbd800000, v29
	v_fmamk_f32 v27, v122, 0xbd800000, v26
	v_cndmask_b32_e64 v23, v23, v24, s[40:41]
	v_cndmask_b32_e32 v24, 0, v161, vcc
	v_sub_f32_e32 v23, v23, v24
	v_fmamk_f32 v24, v123, 0xbd800000, v27
	v_max_f32_e64 v22, -v22, 0
	v_fmamk_f32 v25, v124, 0xbd800000, v24
	v_add_f32_e32 v23, v22, v23
	v_fmamk_f32 v22, v95, 0xbd800000, v25
	v_fmamk_f32 v23, v23, 0xbd800000, v22
	ds_write_b32 v96, v23 offset:59392
	s_waitcnt lgkmcnt(0)
	s_barrier
	ds_read2st64_b32 v[96:97], v110 offset0:232 offset1:233
	ds_read2st64_b32 v[106:107], v110 offset0:234 offset1:235
	s_cselect_b64 vcc, -1, 0
	s_cmp_gt_i32 s42, 1
	s_mov_b64 s[6:7], 0
	s_waitcnt lgkmcnt(1)
	v_add_f32_e32 v95, 0, v96
	v_cndmask_b32_e32 v95, 0, v95, vcc
	v_add_f32_e32 v96, v97, v95
	s_cselect_b64 vcc, -1, 0
	s_cmp_gt_i32 s42, 2
	v_cndmask_b32_e32 v95, v95, v96, vcc
	s_waitcnt lgkmcnt(0)
	v_add_f32_e32 v96, v106, v95
	s_cselect_b64 vcc, -1, 0
	s_cmp_gt_i32 s42, 3
	v_cndmask_b32_e32 v95, v95, v96, vcc
	v_add_f32_e32 v96, v107, v95
	s_cselect_b64 vcc, -1, 0
	v_cndmask_b32_e32 v96, v95, v96, vcc
	v_pk_add_f32 v[22:23], v[22:23], v[96:97] op_sel_hi:[1,0]
	v_pk_add_f32 v[24:25], v[24:25], v[96:97] op_sel_hi:[1,0]
	v_pk_add_f32 v[26:27], v[26:27], v[96:97] op_sel_hi:[1,0]
	v_pk_add_f32 v[28:29], v[28:29], v[96:97] op_sel_hi:[1,0]
	v_pk_add_f32 v[30:31], v[30:31], v[96:97] op_sel_hi:[1,0]
	v_pk_add_f32 v[32:33], v[32:33], v[96:97] op_sel_hi:[1,0]
	v_pk_add_f32 v[34:35], v[34:35], v[96:97] op_sel_hi:[1,0]
	v_pk_add_f32 v[36:37], v[36:37], v[96:97] op_sel_hi:[1,0]

.LBB0_187:
	s_and_b64 vcc, exec, s[6:7]
	s_cbranch_vccz .LBB0_180
	s_mul_hi_i32 s6, s18, 0x2aaaaaab
	s_lshr_b32 s7, s6, 2
	s_lshr_b32 s34, s6, 31
	s_add_i32 s7, s7, s34
	s_mul_i32 s7, s7, 24
	s_sub_i32 s7, s18, s7
	s_mul_i32 s7, s7, 43
	s_add_i32 s6, s6, s34
	s_bfe_u32 s35, s7, 0x1000f
	s_bfe_u32 s7, s7, 0x80008
	s_mul_i32 s6, s6, 6
	s_add_i32 s40, s7, s35
	s_sub_i32 s7, s18, s6
	s_mul_hi_i32 s6, s18, 0xd5555555
	s_lshr_b32 s34, s6, 31
	s_ashr_i32 s73, s6, 2
	s_add_i32 s73, s73, s34
	s_nop 0
	v_mov_b32_e32 v26, v154
	s_add_i32 s72, s73, 63
	s_bfe_i64 s[42:43], s[40:41], 0x80000
	v_readfirstlane_b32 s6, v26
	s_ashr_i32 s6, s6, 6
	s_lshl_b64 s[34:35], s[42:43], 12
	s_lshl_b32 s66, s72, 6
	s_add_u32 s34, s34, s66
	s_addc_u32 s35, s35, 0
	s_lshl_b32 s38, s6, 4
	s_ashr_i32 s36, s38, 31
	v_and_b32_e32 v68, 15, v26
	s_add_u32 s34, s34, s38
	v_or_b32_e32 v0, s34, v68
	v_mov_b64_e32 v[2:3], s[58:59]
	s_addc_u32 s35, s35, s36
	v_mad_u64_u32 v[6:7], s[36:37], v0, s99, v[2:3]
	s_lshl_b32 s36, s7, 6
	s_ashr_i32 s37, s36, 31
	s_lshl_b64 s[36:37], s[36:37], 1
	s_mul_i32 s41, s42, 0x300000
	s_mul_hi_i32 s39, s42, 0x300000
	s_add_u32 s41, s60, s41
	s_addc_u32 s39, s61, s39
	s_add_u32 s42, s41, s36
	s_addc_u32 s43, s39, s37
	s_mul_i32 s39, s40, 6
	s_sext_i32_i8 s39, s39
	s_add_i32 s40, s7, s39
	s_ashr_i32 s41, s40, 31
	s_lshl_b64 s[40:41], s[40:41], 19
	v_lshlrev_b32_e32 v0, 4, v26
	s_add_u32 s40, s62, s40
	v_ashrrev_i32_e32 v54, 3, v26
	v_and_b32_e32 v0, 0x70, v0
	s_addc_u32 s41, s63, s41
	v_lshl_add_u64 v[58:59], s[40:41], 0, v[0:1]
	v_ashrrev_i32_e32 v55, 31, v54
	v_lshl_add_u64 v[8:9], s[66:67], 1, v[58:59]
	v_lshlrev_b64 v[60:61], 13, v[54:55]
	v_add_u32_e32 v12, s66, v54
	v_lshl_add_u64 v[10:11], v[8:9], 0, v[60:61]
	v_lshl_add_u64 v[56:57], s[42:43], 0, v[0:1]
	global_load_dwordx4 v[14:17], v[10:11], off
	v_add_u32_e32 v10, 32, v12
	v_mad_i64_i32 v[2:3], s[40:41], v12, s99, v[56:57]
	v_mad_i64_i32 v[10:11], s[40:41], v10, s99, v[56:57]
	v_mad_i32_i24 v7, s35, v162, v7
	s_mov_b64 s[40:41], 0x40000
	v_lshl_add_u64 v[62:63], v[60:61], 0, s[40:41]
	v_lshl_add_u64 v[6:7], v[6:7], 0, s[36:37]
	v_and_b32_e32 v42, 48, v26
	v_mov_b32_e32 v43, v1
	global_load_dwordx4 v[18:21], v[10:11], off
	v_lshl_add_u64 v[8:9], v[8:9], 0, v[62:63]
	v_lshl_add_u64 v[10:11], v[6:7], 0, v[42:43]
	global_load_dwordx4 v[2:5], v[2:3], off
	s_cmp_eq_u32 s72, 0
	global_load_dwordx4 v[22:25], v[8:9], off
	s_nop 0
	global_load_dwordx4 v[6:9], v[10:11], off
	s_nop 0
	global_load_dwordx4 v[10:13], v[10:11], off offset:64
	s_cselect_b64 s[96:97], -1, 0
	v_mad_u64_u32 v[64:65], s[40:41], v54, s98, v[0:1]
	s_and_b64 vcc, exec, s[96:97]
	s_barrier
	s_waitcnt vmcnt(3)
	ds_write_b128 v64, v[2:5]
	ds_write_b128 v64, v[18:21] offset:4608
	ds_write_b128 v64, v[14:17] offset:9216
	s_waitcnt vmcnt(2)
	ds_write_b128 v64, v[22:25] offset:13824
	s_waitcnt lgkmcnt(0)
	s_barrier
	s_cbranch_vccnz .LBB0_190
	s_sub_i32 s40, s66, 64
	v_add_u32_e32 v0, s40, v54
	s_mov_b32 s41, s67
	v_lshl_add_u64 v[22:23], s[40:41], 1, v[58:59]
	v_mad_i64_i32 v[2:3], s[40:41], v0, s99, v[56:57]
	v_add_u32_e32 v0, 32, v0
	v_lshl_add_u64 v[14:15], v[22:23], 0, v[60:61]
	v_mad_i64_i32 v[18:19], s[40:41], v0, s99, v[56:57]
	v_lshl_add_u64 v[22:23], v[22:23], 0, v[62:63]
	global_load_dwordx4 v[2:5], v[2:3], off
	s_nop 0
	global_load_dwordx4 v[14:17], v[14:15], off
	s_nop 0
	global_load_dwordx4 v[18:21], v[18:19], off
	s_nop 0
	global_load_dwordx4 v[22:25], v[22:23], off
